# P1-P2, P5-P6, P6-P7 grid barriers XCD-local when every workgroup's XCC_ID equals blockIdx&7 (runtime-checked flag, full barrier otherwise)
# speedup vs baseline: 1.0011x; 1.0011x over previous
; #define LAS __attribute__((address_space(3)))
; __device__ __forceinline__ unsigned xb_add(unsigned* p, unsigned v) { return __hip_atomic_fetch_add(p, v, __ATOMIC_RELAXED, __HIP_MEMORY_SCOPE_AGENT); }
; __device__ __forceinline__ unsigned xb_xcc_id() { return (unsigned)__builtin_amdgcn_s_getreg((3 << 11) | 20) & 0xFu; }
; __device__ __forceinline__ XcdBarrier xcd_barrier_post(unsigned* bar, volatile LAS unsigned* st) {
;     XcdBarrier b; b.bar = bar; b.x = xb_xcc_id(); b.st = st;
;     if (threadIdx.x == 0) (void)xb_add(&bar[XB_XCNT(b.x)], 1u);
;     return b;
; }
.LBB0_14:
	s_add_u32 s2, s10, 0x80000
	s_addc_u32 s3, s11, 0
	v_writelane_b32 v235, s2, 8
	v_cmp_eq_u32_e64 s[4:5], 0, v189
	s_nop 0
	v_writelane_b32 v235, s3, 9
	s_getreg_b32 s2, hwreg(HW_REG_XCC_ID, 0, 4)
	s_and_b32 s2, s2, 15
	v_writelane_b32 v235, s2, 10
	s_mov_b64 s[2:3], exec
	v_writelane_b32 v235, s4, 11
	s_nop 1
	v_writelane_b32 v235, s5, 12
	s_and_b64 s[4:5], s[2:3], s[4:5]
	s_mov_b64 exec, s[4:5]
	s_cbranch_execz .LBB0_17
	s_mov_b64 s[4:5], exec
	v_mbcnt_lo_u32_b32 v0, s4, 0
	v_mbcnt_hi_u32_b32 v0, s5, v0
	v_cmp_eq_u32_e32 vcc, 0, v0
	s_and_b64 s[6:7], exec, vcc
	s_mov_b64 exec, s[6:7]
	s_cbranch_execz .LBB0_17
	v_readlane_b32 s6, v235, 10
	s_bcnt1_i32_b64 s4, s[4:5]
	s_lshl_b32 s6, s6, 8
	v_mov_b32_e32 v1, s4
	v_readlane_b32 s4, v235, 8
	v_mov_b32_e32 v0, s6
	v_readlane_b32 s5, v235, 9
	s_nop 4
	global_atomic_add v0, v1, s[4:5] offset:1024
	v_readlane_b32 s6, v235, 10
	v_readlane_b32 s7, v235, 0
	s_nop 0
	s_and_b32 s7, s7, 7
	s_cmp_lg_u32 s6, s7
	s_cbranch_scc0 .Lxg_ok
	v_mov_b32_e32 v0, 0x3800
	global_atomic_add v0, v1, s[4:5]
.Lxg_ok:
.LBB0_17:
	s_or_b64 exec, exec, s[2:3]
	v_readlane_b32 s2, v235, 0
	v_mov_b32_e32 v8, v189
	s_lshl_b32 s2, s2, 9
	v_writelane_b32 v235, s2, 13
	v_add_u32_e32 v4, s2, v8
	s_load_dwordx2 s[2:3], s[0:1], 0xb0
	s_load_dwordx16 s[12:27], s[0:1], 0x0
	s_mov_b32 s4, 0x10000
	v_cmp_gt_i32_e32 vcc, s4, v4
	s_waitcnt lgkmcnt(0)
	s_lshl_b32 s94, s2, 9
	s_and_saveexec_b64 s[2:3], vcc
	s_cbranch_execz .LBB0_25
	v_cvt_f32_u32_e32 v0, s94
	v_add_u32_e32 v5, s94, v4
	v_mov_b32_e32 v1, s94
	v_cmp_gt_i32_e32 vcc, s4, v5
	v_rcp_iflag_f32_e32 v0, v0
	s_sub_i32 s6, 0, s94
	v_max_i32_e32 v2, 0x10000, v5
	v_addc_co_u32_e64 v1, s[4:5], v4, v1, vcc
	v_mul_f32_e32 v0, 0x4f7ffffe, v0
	v_cvt_u32_f32_e32 v0, v0
	v_sub_u32_e32 v1, v2, v1
	v_mul_lo_u32 v2, s6, v0
	v_mul_hi_u32 v2, v0, v2
	v_add_u32_e32 v0, v0, v2
	v_mul_hi_u32 v0, v1, v0
	v_mul_lo_u32 v2, v0, s94
	v_sub_u32_e32 v1, v1, v2
	v_add_u32_e32 v3, 1, v0
	v_cmp_le_u32_e64 s[4:5], s94, v1
	v_subrev_u32_e32 v2, s94, v1
	s_mov_b64 s[6:7], -1
	v_cndmask_b32_e64 v0, v0, v3, s[4:5]
	v_cndmask_b32_e64 v1, v1, v2, s[4:5]
	v_add_u32_e32 v2, 1, v0
	v_cmp_le_u32_e64 s[4:5], s94, v1
	s_nop 1
	v_cndmask_b32_e64 v0, v0, v2, s[4:5]
	v_addc_co_u32_e32 v2, vcc, 1, v0, vcc
	v_cmp_lt_u32_e32 vcc, 1, v2
	v_mov_b32_e32 v0, v4
	s_and_saveexec_b64 s[4:5], vcc
	s_cbranch_execz .LBB0_22
	s_load_dwordx2 s[6:7], s[0:1], 0xb0
	s_load_dwordx4 s[44:47], s[0:1], 0xa0
	v_and_b32_e32 v3, -2, v2
	v_mov_b32_e32 v6, 0
	v_mov_b32_e32 v7, v3
	s_waitcnt lgkmcnt(0)
	s_lshl_b32 s8, s6, 10
	s_mov_b32 s9, s8
	s_mov_b64 s[6:7], 0
	v_mov_b64_e32 v[0:1], v[4:5]

; #define PG8_WAIT_V(n) asm volatile("s_waitcnt vmcnt(" #n ")" ::: "memory")
; #define PG8_BAR __builtin_amdgcn_s_barrier()
; template <class Epi, class Sched, bool ALIGN_EPI = false, bool SP2 = false>
; __device__ __forceinline__ void gemm_phase(PG8_LAS unsigned char* lds, const Gemm g, const Sched& S, const Epi& E) {
;     ...
;     const int wid = __builtin_amdgcn_readfirstlane(tid >> 6), lane = tid & 63, wr = wid >> 2, wc = wid & 3, fr = lane & 15, fq = lane >> 4;
;     const int K = g.K, nt = K / BK;
;     unsigned voffA[2], voffB[2];
; #pragma unroll
;     for (int i = 0; i < 2; ++i) { int R, C; stage_rc(tid * 16 + i * 8192, R, C); const int Rb = Epi::PERM ? ((R & ~31) + perm32(R & 31)) : R;
;         voffA[i] = (unsigned)(R * K + C) * 2u; voffB[i] = (unsigned)(Rb * K + C) * 2u; }
;     const size_t kstep = (size_t)(BK * 2);
;     const size_t hstep = (size_t)HALF * K * 2;
;     const size_t tstep = 2 * hstep;
;     const unsigned ldsw = (unsigned)wid * 1024u;
;     const int aoff = lds_byte(wr * 64 + fr, fq * 8), boff = lds_byte(wc * 32 + fr, fq * 8);
;     ...
;     Unit cur, nxt; int ui = 0;
;     if (!S.next(0, cur)) return;
;     f32x4 acc[2][2][4][2];
; #pragma unroll
;     for (int a = 0; a < 2; ++a)
; #pragma unroll
;         for (int b = 0; b < 2; ++b)
; #pragma unroll
;             for (int m = 0; m < 4; ++m)
; #pragma unroll
;                 for (int n = 0; n < 2; ++n) acc[a][b][m][n] = (f32x4){0.f, 0.f, 0.f, 0.f};
;     bf16x8 At[4][2], B0[2][2], B1[2][2];
;     const char* cA = (const char*)g.A + (size_t)cur.pm * tstep; const char* cB = (const char*)g.Bt + (size_t)cur.pn * tstep;
;     S.a_ready(cur);
;     if constexpr (SP2) {
;         PG8_STAGE(PG8_SB(0, 0), cB, voffB); PG8_STAGE(PG8_SB(0, 1), cB + hstep, voffB); PG8_STAGE(PG8_SA(0, 0), cA, voffA); PG8_STAGE(PG8_SA(0, 1), cA + hstep, voffA);
;         if (wr == 1) PG8_BAR;
;         PG8_WAIT_V(2); PG8_BAR;
;         PG8_STAGE(PG8_SB(1, 0), cB + kstep, voffB); PG8_STAGE(PG8_SA(1, 0), cA + kstep, voffA); PG8_STAGE(PG8_SB(1, 1), cB + hstep + kstep, voffB);
;         PG8_WAIT_V(6); PG8_BAR;
;     } else {
;         PG8_STAGE(PG8_SB(0, 0), cB, voffB); PG8_STAGE(PG8_SA(0, 0), cA, voffA); PG8_STAGE(PG8_SB(0, 1), cB + hstep, voffB); PG8_STAGE(PG8_SA(0, 1), cA + hstep, voffA);
;         if (wr == 1) PG8_BAR;
;         PG8_WAIT_V(4); PG8_BAR;
.LBB0_183:
	s_or_b64 exec, exec, s[0:1]
	v_readlane_b32 s4, v235, 8
	v_readlane_b32 s5, v235, 9
	v_mov_b32_e32 v0, 0x3800
	s_nop 3
	global_load_dword v1, v0, s[4:5] sc1
	v_mov_b32_e32 v0, 0x20170
	s_waitcnt vmcnt(0)
	ds_write_b32 v0, v1
	v_readlane_b32 s0, v235, 2
	v_readlane_b32 s2, v235, 4
	v_readlane_b32 s1, v235, 3
	v_readlane_b32 s3, v235, 5
	s_add_u32 s0, s2, 0x7000000
	s_addc_u32 s1, s3, 0
	v_writelane_b32 v235, s0, 33
	v_mov_b32_e32 v9, v189
	s_waitcnt lgkmcnt(0)
	v_writelane_b32 v235, s1, 34
	s_barrier
	v_readlane_b32 s0, v235, 0
	s_cmpk_lt_i32 s0, 0xb00
	s_cselect_b64 s[2:3], -1, 0
	v_writelane_b32 v235, s2, 35
	s_cmpk_gt_i32 s0, 0xaff
	v_readfirstlane_b32 s1, v9
	v_writelane_b32 v235, s3, 36
	s_cbranch_scc1 .LBB0_199
	v_lshlrev_b32_e32 v0, 4, v9
	v_add_u32_e32 v1, 0x2000, v0
	v_ashrrev_i32_e32 v2, 31, v1
	v_lshrrev_b32_e32 v2, 22, v2
	v_add_u32_e32 v2, v1, v2
	v_ashrrev_i32_e32 v8, 10, v2
	v_mul_i32_i24_e32 v2, 0x400, v8
	v_sub_u32_e32 v1, v1, v2
	v_lshrrev_b32_e32 v2, 4, v1
	v_bitop3_b32 v1, v2, v1, 32 bitop3:0x6c
	v_ashrrev_i32_e32 v2, 31, v1
	v_lshrrev_b32_e32 v2, 26, v2
	v_add_u32_e32 v2, v1, v2
	v_lshlrev_b32_e32 v3, 3, v8
	v_ashrrev_i32_e32 v10, 6, v2
	v_and_b32_e32 v3, -16, v3
	v_add_u32_e32 v3, v10, v3
	v_and_b32_e32 v4, 3, v10
	s_mov_b32 s0, 0x1fffe0
	v_lshrrev_b32_e32 v5, 2, v3
	v_lshlrev_b32_e32 v6, 1, v3
	v_and_b32_e32 v2, 0xc0, v2
	v_and_or_b32 v4, v3, s0, v4
	v_and_b32_e32 v5, 4, v5
	v_and_b32_e32 v6, 24, v6
	v_sub_u32_e32 v1, v1, v2
	v_mov_b32_e32 v2, 1
	v_or3_b32 v4, v4, v5, v6
	v_lshlrev_b32_e32 v5, 5, v8
	v_ashrrev_i16_sdwa v1, v2, sext(v1) dst_sel:DWORD dst_unused:UNUSED_PAD src0_sel:DWORD src1_sel:BYTE_0
	v_and_b32_e32 v5, 32, v5
	v_bfe_i32 v11, v1, 0, 16
	v_add_lshl_u32 v1, v5, v11, 1
	v_lshl_add_u32 v128, v4, 11, v1
	v_lshl_add_u32 v130, v3, 11, v1
	v_bfe_i32 v1, v9, 27, 1
	v_lshrrev_b32_e32 v1, 22, v1
	v_add_u32_e32 v1, v0, v1
	v_and_b32_e32 v1, 0xfffffc00, v1
	v_sub_u32_e32 v0, v0, v1
	v_lshrrev_b32_e32 v1, 4, v0
	v_ashrrev_i32_e32 v3, 31, v9
	v_bitop3_b32 v0, v1, v0, 32 bitop3:0x6c
	v_lshrrev_b32_e32 v3, 26, v3
	v_ashrrev_i32_e32 v1, 31, v0
	v_add_u32_e32 v3, v9, v3
	v_readlane_b32 s4, v235, 2
	v_lshrrev_b32_e32 v1, 26, v1
	v_ashrrev_i32_e32 v13, 6, v3
	v_readlane_b32 s6, v235, 4
	v_add_u32_e32 v1, v0, v1
	v_lshlrev_b32_e32 v3, 3, v13
	v_readlane_b32 s7, v235, 5
	s_add_u32 s33, s6, 0x200000
	v_ashrrev_i32_e32 v12, 6, v1
	v_and_b32_e32 v3, -16, v3
	v_readlane_b32 s3, v235, 0
	s_addc_u32 s34, s7, 0
	v_add_u32_e32 v3, v12, v3
	v_and_b32_e32 v4, 3, v12
	s_ashr_i32 s36, s3, 31
	v_and_or_b32 v4, v3, s0, v4
	s_lshr_b32 s0, s36, 29
	s_add_i32 s0, s3, s0
	s_ashr_i32 s4, s1, 6
	s_ashr_i32 s2, s0, 3
	s_and_b32 s0, s0, -8
	s_ashr_i32 s6, s1, 8
	s_lshl_b32 s35, s4, 10
	s_sub_i32 s0, s3, s0
	s_cmp_lt_i32 s0, 0
	s_movk_i32 s37, 0x161
	s_cselect_b32 s3, s37, 0x160
	s_mul_i32 s0, s0, s3
	s_add_i32 s0, s0, s2
	s_mul_hi_i32 s2, s0, 0x2e8ba2e9
	s_lshr_b32 s3, s2, 31
	s_ashr_i32 s2, s2, 4
	s_add_i32 s2, s2, s3
	s_lshl_b32 s3, s2, 2
	s_mulk_i32 s2, 0x58
	s_sub_i32 s2, s0, s2
	s_bfe_i32 s0, s2, 0x80000
	v_readlane_b32 s5, v235, 3
	s_bfe_u32 s0, s0, 0x2000d
	s_add_i32 s5, s2, s0
	s_bfe_i32 s0, s5, 0x80000
	s_and_b32 s5, s5, 0xfc
	s_sub_i32 s2, s2, s5
	s_sext_i32_i16 s0, s0
	s_sext_i32_i8 s2, s2
	v_lshrrev_b32_e32 v5, 2, v3
	v_lshlrev_b32_e32 v6, 1, v3
	v_and_b32_e32 v1, 0xc0, v1
	s_lshr_b32 s0, s0, 2
	s_add_i32 s20, s3, s2
	v_and_b32_e32 v5, 4, v5
	v_and_b32_e32 v6, 24, v6
	v_sub_u32_e32 v0, v0, v1
	s_ashr_i32 s21, s20, 31
	s_bfe_i64 s[8:9], s[0:1], 0x100000
	v_or3_b32 v4, v4, v5, v6
	v_lshlrev_b32_e32 v5, 5, v13
	v_ashrrev_i16_sdwa v0, v2, sext(v0) dst_sel:DWORD dst_unused:UNUSED_PAD src0_sel:DWORD src1_sel:BYTE_0
	s_lshl_b64 s[2:3], s[20:21], 19
	s_lshl_b64 s[8:9], s[8:9], 19
	v_and_b32_e32 v5, 32, v5
	v_bfe_i32 v14, v0, 0, 16
	s_add_u32 s24, s33, s8
	v_add_lshl_u32 v0, v5, v14, 1
	s_addc_u32 s25, s34, s9
	s_add_i32 s21, s35, 0
	v_lshl_add_u32 v132, v4, 11, v0
	s_add_i32 m0, s21, 0x10000
	v_lshl_add_u32 v134, v3, 11, v0
	global_load_lds_dwordx4 v132, s[24:25]
	s_add_i32 m0, s21, 0x12000
	s_add_u32 s8, s24, 0x40000
	global_load_lds_dwordx4 v128, s[24:25]
	s_addc_u32 s9, s25, 0
	s_add_i32 m0, s21, 0x14000
	v_mov_b32_e32 v133, 0
	global_load_lds_dwordx4 v132, s[8:9]
	s_add_i32 m0, s21, 0x16000
	v_mov_b32_e32 v129, v133
	global_load_lds_dwordx4 v128, s[8:9]
	v_readlane_b32 s8, v235, 31
	v_readlane_b32 s9, v235, 32
	s_add_u32 s22, s8, s2
	s_addc_u32 s23, s9, s3
	s_add_i32 s38, s21, 0x2000
	s_mov_b32 m0, s21
	s_add_u32 s2, s22, 0x40000
	global_load_lds_dwordx4 v134, s[22:23]
	s_mov_b32 m0, s38
	s_addc_u32 s3, s23, 0
	s_add_i32 s39, s21, 0x4000
	global_load_lds_dwordx4 v130, s[22:23]
	s_mov_b32 m0, s39
	s_add_i32 s40, s21, 0x6000
	global_load_lds_dwordx4 v134, s[2:3]
	s_mov_b32 m0, s40
	v_mov_b32_e32 v135, v133
	global_load_lds_dwordx4 v130, s[2:3]
	v_mov_b32_e32 v131, v133
	s_cmp_eq_u32 s6, 1
	s_mov_b32 s41, 0
	v_lshl_add_u64 v[6:7], s[24:25], 0, v[132:133]
	v_lshl_add_u64 v[4:5], s[24:25], 0, v[128:129]
	v_lshl_add_u64 v[0:1], s[22:23], 0, v[134:135]
	s_cselect_b64 s[2:3], -1, 0
	s_cmp_lg_u32 s6, 1
	v_lshl_add_u64 v[2:3], s[22:23], 0, v[130:131]
	s_cbranch_scc1 .LBB0_186
	s_barrier

; __device__ __forceinline__ unsigned xb_add(unsigned* p, unsigned v) { return __hip_atomic_fetch_add(p, v, __ATOMIC_RELAXED, __HIP_MEMORY_SCOPE_AGENT); }
; __device__ __forceinline__ void xcd_barrier(const XcdBarrier& b) {
;     ...
;         const unsigned old = xb_add(&bar[XB_XSUB(b.x)], 1u);
;         const unsigned gen = old / nloc;
;         if (old + 1u == (gen + 1u) * nloc) {
;             __builtin_amdgcn_fence(__ATOMIC_RELEASE, "agent");
;             asm volatile("s_waitcnt vmcnt(0)" ::: "memory");
;             const unsigned og = xb_add(&bar[XB_TOP], 1u);
;             const unsigned tg = og / nx;
;             if (og + 1u == (tg + 1u) * nx) xb_add(&bar[XB_TOPGEN], 1u);
.LBB0_231:
	s_andn2_saveexec_b64 s[4:5], s[4:5]
	s_cbranch_execz .LBB0_251
	s_mov_b64 s[4:5], exec
	v_mov_b32_e32 v20, 0x20170
	ds_read_b32 v20, v20
	s_waitcnt lgkmcnt(0)
	v_readfirstlane_b32 s6, v20
	s_nop 0
	s_cmp_eq_u32 s6, 0
	s_cbranch_scc1 .LBB0_248
	buffer_wbl2 sc1
	s_waitcnt lgkmcnt(0)
	s_waitcnt vmcnt(0)
	v_mbcnt_lo_u32_b32 v1, s4, 0
	v_mbcnt_hi_u32_b32 v1, s5, v1
	v_cmp_eq_u32_e32 vcc, 0, v1
	s_and_saveexec_b64 s[6:7], vcc
	s_cbranch_execz .LBB0_234
	s_bcnt1_i32_b64 s4, s[4:5]
	v_readlane_b32 s16, v235, 2
	v_mov_b32_e32 v2, 0x83000
	v_mov_b32_e32 v3, s4
	v_readlane_b32 s18, v235, 4
	v_readlane_b32 s19, v235, 5
	v_readlane_b32 s17, v235, 3
	s_nop 3
	global_atomic_add v2, v2, v3, s[18:19] offset:1024 sc0

; __device__ __forceinline__ unsigned xb_add(unsigned* p, unsigned v) { return __hip_atomic_fetch_add(p, v, __ATOMIC_RELAXED, __HIP_MEMORY_SCOPE_AGENT); }
; __device__ __forceinline__ void xcd_barrier(const XcdBarrier& b) {
;     ...
;         const unsigned old = xb_add(&bar[XB_XSUB(b.x)], 1u);
;         const unsigned gen = old / nloc;
;         if (old + 1u == (gen + 1u) * nloc) {
;             __builtin_amdgcn_fence(__ATOMIC_RELEASE, "agent");
;             asm volatile("s_waitcnt vmcnt(0)" ::: "memory");
;             const unsigned og = xb_add(&bar[XB_TOP], 1u);
;             const unsigned tg = og / nx;
;             if (og + 1u == (tg + 1u) * nx) xb_add(&bar[XB_TOPGEN], 1u);
.LBB0_753:
	s_andn2_saveexec_b64 s[4:5], s[4:5]
	s_cbranch_execz .LBB0_773
	s_mov_b64 s[4:5], exec
	v_mov_b32_e32 v20, 0x20170
	ds_read_b32 v20, v20
	s_waitcnt lgkmcnt(0)
	v_readfirstlane_b32 s6, v20
	s_nop 0
	s_cmp_eq_u32 s6, 0
	s_cbranch_scc1 .LBB0_770
	buffer_wbl2 sc1
	s_waitcnt lgkmcnt(0)
	s_waitcnt vmcnt(0)
	v_mbcnt_lo_u32_b32 v1, s4, 0
	v_mbcnt_hi_u32_b32 v1, s5, v1
	v_cmp_eq_u32_e32 vcc, 0, v1
	s_and_saveexec_b64 s[6:7], vcc
	s_cbranch_execz .LBB0_756
	s_bcnt1_i32_b64 s4, s[4:5]
	v_readlane_b32 s12, v235, 2
	v_mov_b32_e32 v2, 0x83000
	v_mov_b32_e32 v3, s4
	v_readlane_b32 s14, v235, 4
	v_readlane_b32 s15, v235, 5
	v_readlane_b32 s13, v235, 3
	s_nop 3
	global_atomic_add v2, v2, v3, s[14:15] offset:1024 sc0
